# GEMM loop: per-phase s_setprio flips removed, one static s_setprio 1 for waves 4-7 for the whole GEMM phase
# baseline (speedup 1.0000x reference)
; #define PG8_STAGE(bufoff, gbase, voff) do { _Pragma("unroll") for (int _i = 0; _i < 2; ++_i) \
;         __builtin_amdgcn_global_load_lds((const unsigned*)((const char*)(gbase) + (voff)[_i]), (LAS unsigned*)(lds + (bufoff) + ldsw + _i * 8192), 16, 0, 0); } while (0)
; #define PG8_WAIT_V(n) asm volatile("s_waitcnt vmcnt(" #n ")" ::: "memory")
; #define PG8_BAR __builtin_amdgcn_s_barrier()
; template <class Epi>
; __device__ __forceinline__ void gemm_phase(LAS unsigned char* lds, const Gemm g, const StaticOrder& S, const Epi& E, const bool perm) {
;     ...
;     for (int i = 0; i < 2; ++i) { int R, C; stage_rc(tid * 16 + i * 8192, R, C); const int Rb = perm ? ((R & ~31) + perm32(R & 31)) : R;
;         voffA[i] = (unsigned)(R * K + C) * 2u; voffB[i] = (unsigned)(Rb * K + C) * 2u; }
;     const size_t kstep = (size_t)(BK * 2);
;     const size_t hstep = (size_t)HALF * K * 2;
;     const size_t tstep = 2 * hstep;
;     const unsigned ldsw = (unsigned)wid * 1024u;
;     const int aoff = lds_byte(wr * 64 + fr, fq * 8), boff = lds_byte(wc * 32 + fr, fq * 8);
;     ...
;     const char* cA = (const char*)g.A + (size_t)cur.pm * tstep; const char* cB = (const char*)g.Bt + (size_t)cur.pn * tstep;
;     PG8_STAGE(PG8_SB(0, 0), cB, voffB); PG8_STAGE(PG8_SA(0, 0), cA, voffA); PG8_STAGE(PG8_SB(0, 1), cB + hstep, voffB); PG8_STAGE(PG8_SA(0, 1), cA + hstep, voffA);
;     if (wr == 1) PG8_BAR;
;     PG8_WAIT_V(4); PG8_BAR;
;     PG8_STAGE(PG8_SB(1, 0), cB + kstep, voffB); PG8_STAGE(PG8_SA(1, 0), cA + kstep, voffA); PG8_STAGE(PG8_SB(1, 1), cB + hstep + kstep, voffB);
;     PG8_WAIT_V(6); PG8_BAR;
.LBB0_450:
	s_and_b64 vcc, exec, s[0:1]
	s_cbranch_vccz .LBB0_766
	v_readlane_b32 s0, v255, 59
	s_ashr_i32 s9, s0, 6
	s_ashr_i32 s8, s0, 8
	s_lshl_b64 s[82:83], s[24:25], 9
	s_ashr_i32 s0, s46, 31
	s_mul_i32 s0, s82, s0
	s_mul_hi_u32 s1, s82, s46
	s_ashr_i32 s7, s70, 31
	v_mul_i32_i24_e32 v7, 64, v7
	s_add_i32 s0, s1, s0
	s_lshr_b32 s1, s24, 23
	s_mul_i32 s7, s82, s7
	s_mul_hi_u32 s11, s82, s70
	v_mov_b32_e32 v11, 1
	v_sub_u32_e32 v4, v4, v7
	s_mul_i32 s6, s1, s46
	s_add_i32 s7, s11, s7
	s_mul_i32 s1, s1, s70
	v_lshlrev_b32_e32 v9, 6, v9
	s_lshl_b64 s[80:81], s[24:25], 8
	s_lshl_b32 s31, s9, 10
	v_lshlrev_b32_e32 v2, 5, v2
	v_ashrrev_i16_sdwa v4, v11, sext(v4) dst_sel:DWORD dst_unused:UNUSED_PAD src0_sel:DWORD src1_sel:BYTE_0
	s_add_i32 s0, s0, s6
	s_add_i32 s7, s7, s1
	s_mul_i32 s1, s82, s70
	v_sub_u32_e32 v3, v3, v9
	v_and_b32_e32 v2, 32, v2
	v_bfe_i32 v4, v4, 0, 16
	s_add_u32 s22, s48, s1
	v_lshlrev_b32_e32 v1, 5, v1
	v_ashrrev_i16_sdwa v3, v11, sext(v3) dst_sel:DWORD dst_unused:UNUSED_PAD src0_sel:DWORD src1_sel:BYTE_0
	v_add_u32_e32 v7, v2, v4
	v_mul_lo_u32 v8, v8, s24
	s_addc_u32 s23, s49, s7
	s_add_i32 s36, s31, 0
	s_and_b32 s98, s70, 3
	s_lshl_b32 s98, s98, 8
	s_cmp_eq_u32 s5, 7
	s_cselect_b32 s98, s98, 0
	s_add_u32 s22, s22, s98
	s_addc_u32 s23, s23, 0
	v_and_b32_e32 v1, 32, v1
	v_bfe_i32 v3, v3, 0, 16
	v_add_lshl_u32 v212, v8, v7, 1
	s_add_i32 m0, s36, 0x10000
	v_add_u32_e32 v9, v1, v3
	v_mul_lo_u32 v10, v10, s24
	s_mul_i32 s6, s82, s46
	global_load_lds_dwordx4 v212, s[22:23]
	s_add_i32 m0, s36, 0x12000
	v_add_lshl_u32 v208, v10, v9, 1
	v_mul_lo_u32 v5, v5, s24
	s_add_u32 s6, s28, s6
	v_mul_lo_u32 v6, v6, s24
	v_add_lshl_u32 v210, v7, v5, 1
	global_load_lds_dwordx4 v208, s[22:23]
	s_addc_u32 s7, s29, s0
	s_add_u32 s6, s6, s98
	s_addc_u32 s7, s7, 0
	s_mov_b32 m0, s36
	s_add_i32 s37, s36, 0x2000
	v_add_lshl_u32 v206, v9, v6, 1
	global_load_lds_dwordx4 v210, s[6:7]
	s_mov_b32 m0, s37
	s_add_u32 s0, s22, s80
	global_load_lds_dwordx4 v206, s[6:7]
	s_addc_u32 s1, s23, s81
	s_add_i32 m0, s36, 0x14000
	s_nop 0
	global_load_lds_dwordx4 v212, s[0:1]
	s_add_i32 m0, s36, 0x16000
	s_add_u32 s12, s6, s80
	s_addc_u32 s13, s7, s81
	s_add_i32 s34, s36, 0x4000
	global_load_lds_dwordx4 v208, s[0:1]
	s_mov_b32 m0, s34
	s_add_i32 s35, s36, 0x6000
	global_load_lds_dwordx4 v210, s[12:13]
	s_mov_b32 m0, s35
	s_cmp_lg_u32 s8, 1
	global_load_lds_dwordx4 v206, s[12:13]
	s_cbranch_scc1 .LBB0_453
	s_barrier
	s_setprio 1

; #define PG8_STAGE(bufoff, gbase, voff) do { _Pragma("unroll") for (int _i = 0; _i < 2; ++_i) \
;         __builtin_amdgcn_global_load_lds((const unsigned*)((const char*)(gbase) + (voff)[_i]), (LAS unsigned*)(lds + (bufoff) + ldsw + _i * 8192), 16, 0, 0); } while (0)
; #define PG8_LDA(dst, b, h) do { _Pragma("unroll") for (int m = 0; m < 4; ++m) _Pragma("unroll") for (int k = 0; k < 2; ++k) dst[m][k] = *(const LAS bf16x8*)(lds + PG8_SA(b, h) + aoff + m * 2048 + k * 1024); } while (0)
; #define PG8_LDB(dst, b, h) do { _Pragma("unroll") for (int n = 0; n < 2; ++n) _Pragma("unroll") for (int k = 0; k < 2; ++k) dst[n][k] = *(const LAS bf16x8*)(lds + PG8_SB(b, h) + boff + n * 2048 + k * 1024); } while (0)
; #define PG8_MMA(ai, bj, At, Bt) do { __builtin_amdgcn_s_setprio(1); _Pragma("unroll") for (int m = 0; m < 4; ++m) _Pragma("unroll") for (int n = 0; n < 2; ++n) _Pragma("unroll") for (int k = 0; k < 2; ++k) \
;         acc[ai][bj][m][n] = __builtin_amdgcn_mfma_f32_16x16x32_bf16(Bt[n][k], At[m][k], acc[ai][bj][m][n], 0, 0, 0); __builtin_amdgcn_s_setprio(0); } while (0)
; #define PG8_WAIT_L(n) asm volatile("s_waitcnt lgkmcnt(" #n ")" ::: "memory")
; #define PG8_BAR __builtin_amdgcn_s_barrier()
; #define PG8_SCHED __builtin_amdgcn_sched_barrier(0)
; template <class Epi>
; __device__ __forceinline__ void gemm_phase(LAS unsigned char* lds, const Gemm g, const StaticOrder& S, const Epi& E, const bool perm) {
;     ...
;             PG8_LDB(B0, 0, 0); PG8_SCHED; PG8_LDA(At, 0, 0); PG8_STAGE(PG8_SA(1, 1), a1 + hstep, voffA);
;             PG8_WAIT_L(8); PG8_BAR; PG8_WAIT_L(0); PG8_MMA(0, 0, At, B0); PG8_BAR; PG8_SCHED;
;             PG8_LDB(B1, 0, 1); PG8_STAGE(PG8_SB(0, 0), b2, voffB);
;             PG8_BAR; PG8_WAIT_L(0); PG8_MMA(0, 1, At, B1); PG8_BAR;
;             PG8_LDA(At, 0, 1); PG8_STAGE(PG8_SA(0, 0), a2, voffA);
.Lk_first:
	s_add_i32 s61, s60, 2
	s_add_u32 s22, s6, 0x80
	s_addc_u32 s23, s7, 0
	s_add_i32 s40, 0, 0x10000
	v_add_u32_e32 v140, s40, v245
	s_waitcnt lgkmcnt(0)
	ds_read_b128 v[128:131], v140
	ds_read_b128 v[132:135], v140 offset:1024
	ds_read_b128 v[136:139], v140 offset:2048
	ds_read_b128 v[140:143], v140 offset:3072
	s_cmp_eq_u32 s27, s60
	s_cselect_b32 s23, s1, s23
	s_cselect_b32 s22, s0, s22
	s_cselect_b32 s47, s13, s78
	s_cselect_b32 s46, s12, s55
	v_lshl_add_u64 v[176:177], s[6:7], 0, v[214:215]
	s_add_i32 m0, s36, 0xc000
	ds_read_b128 v[144:147], v248
	ds_read_b128 v[148:151], v248 offset:1024
	ds_read_b128 v[152:155], v248 offset:2048
	ds_read_b128 v[156:159], v248 offset:3072
	ds_read_b128 v[160:163], v248 offset:4096
	ds_read_b128 v[164:167], v248 offset:5120
	ds_read_b128 v[168:171], v248 offset:6144
	ds_read_b128 v[172:175], v248 offset:7168
	global_load_lds_dwordx4 v[176:177], off
	v_lshl_add_u64 v[176:177], s[6:7], 0, v[216:217]
	s_add_i32 m0, s36, 0xe000
	s_nop 0
	global_load_lds_dwordx4 v[176:177], off
	s_add_i32 s60, 0, 0x14000
	s_add_i32 s40, s40, s31
	v_add_u32_e32 v184, s60, v245
	ds_read_b128 v[176:179], v184
	ds_read_b128 v[180:183], v184 offset:1024
	ds_read_b128 v[222:225], v184 offset:2048
	ds_read_b128 v[226:229], v184 offset:3072
	s_waitcnt vmcnt(8)
	s_waitcnt lgkmcnt(0)
	s_barrier
	v_mfma_f32_16x16x32_bf16 v[124:127], v[128:131], v[144:147], 0
	v_mfma_f32_16x16x32_bf16 v[120:123], v[136:139], v[144:147], 0
	v_mfma_f32_16x16x32_bf16 v[108:111], v[128:131], v[152:155], 0
	v_mfma_f32_16x16x32_bf16 v[104:107], v[136:139], v[152:155], 0
	v_mfma_f32_16x16x32_bf16 v[92:95], v[128:131], v[160:163], 0
	v_mfma_f32_16x16x32_bf16 v[88:91], v[136:139], v[160:163], 0
	v_mfma_f32_16x16x32_bf16 v[76:79], v[128:131], v[168:171], 0
	v_mfma_f32_16x16x32_bf16 v[72:75], v[136:139], v[168:171], 0
	v_mfma_f32_16x16x32_bf16 v[124:127], v[132:135], v[148:151], v[124:127]
	v_mfma_f32_16x16x32_bf16 v[120:123], v[140:143], v[148:151], v[120:123]
	v_mfma_f32_16x16x32_bf16 v[108:111], v[132:135], v[156:159], v[108:111]
	v_mfma_f32_16x16x32_bf16 v[104:107], v[140:143], v[156:159], v[104:107]
	v_mfma_f32_16x16x32_bf16 v[92:95], v[132:135], v[164:167], v[92:95]
	v_mfma_f32_16x16x32_bf16 v[88:91], v[140:143], v[164:167], v[88:91]
	v_mfma_f32_16x16x32_bf16 v[76:79], v[132:135], v[172:175], v[76:79]
	v_mfma_f32_16x16x32_bf16 v[72:75], v[140:143], v[172:175], v[72:75]
	v_mfma_f32_16x16x32_bf16 v[116:119], v[176:179], v[144:147], 0
	v_mfma_f32_16x16x32_bf16 v[112:115], v[222:225], v[144:147], 0
	v_mfma_f32_16x16x32_bf16 v[100:103], v[176:179], v[152:155], 0
	v_mfma_f32_16x16x32_bf16 v[96:99], v[222:225], v[152:155], 0
	v_mfma_f32_16x16x32_bf16 v[84:87], v[176:179], v[160:163], 0
	v_mfma_f32_16x16x32_bf16 v[80:83], v[222:225], v[160:163], 0
	v_mfma_f32_16x16x32_bf16 v[68:71], v[176:179], v[168:171], 0
	v_mfma_f32_16x16x32_bf16 v[64:67], v[222:225], v[168:171], 0
	v_mfma_f32_16x16x32_bf16 v[116:119], v[180:183], v[148:151], v[116:119]
	v_mfma_f32_16x16x32_bf16 v[112:115], v[226:229], v[148:151], v[112:115]
	v_mfma_f32_16x16x32_bf16 v[100:103], v[180:183], v[156:159], v[100:103]
	v_mfma_f32_16x16x32_bf16 v[96:99], v[226:229], v[156:159], v[96:99]
	v_mfma_f32_16x16x32_bf16 v[84:87], v[180:183], v[164:167], v[84:87]
	v_mfma_f32_16x16x32_bf16 v[80:83], v[226:229], v[164:167], v[80:83]
	v_mfma_f32_16x16x32_bf16 v[68:71], v[180:183], v[172:175], v[68:71]
	v_mfma_f32_16x16x32_bf16 v[64:67], v[226:229], v[172:175], v[64:67]
	s_barrier
	ds_read_b128 v[144:147], v248 offset:16384
	ds_read_b128 v[148:151], v248 offset:17408
	ds_read_b128 v[152:155], v248 offset:18432
	ds_read_b128 v[156:159], v248 offset:19456
	ds_read_b128 v[160:163], v248 offset:20480
	ds_read_b128 v[164:167], v248 offset:21504
	ds_read_b128 v[168:171], v248 offset:22528
	ds_read_b128 v[172:175], v248 offset:23552
	v_lshl_add_u64 v[230:231], s[46:47], 0, v[212:213]
	s_mov_b32 m0, s40
	s_nop 0
	global_load_lds_dwordx4 v[230:231], off
	v_lshl_add_u64 v[232:233], s[46:47], 0, v[208:209]
	s_add_i32 m0, s40, 0x2000
	s_nop 0
	global_load_lds_dwordx4 v[232:233], off
	v_lshl_add_u64 v[250:251], s[22:23], 0, v[210:211]
	s_mov_b32 m0, s36
	s_nop 0
	global_load_lds_dwordx4 v[250:251], off
	v_lshl_add_u64 v[252:253], s[22:23], 0, v[206:207]
	s_mov_b32 m0, s37
	s_nop 0
	global_load_lds_dwordx4 v[252:253], off
	s_add_u32 s40, s46, s80
	s_addc_u32 s41, s47, s81
	s_add_i32 s46, s60, s31
	v_lshl_add_u64 v[238:239], s[40:41], 0, v[212:213]
	s_mov_b32 m0, s46
	v_lshl_add_u64 v[240:241], s[40:41], 0, v[208:209]
	global_load_lds_dwordx4 v[238:239], off
	s_add_i32 m0, s46, 0x2000
	s_nop 0
	global_load_lds_dwordx4 v[240:241], off
	s_waitcnt vmcnt(8)
	s_waitcnt lgkmcnt(0)
	s_barrier
; #define PG8_STAGE(bufoff, gbase, voff) do { _Pragma("unroll") for (int _i = 0; _i < 2; ++_i) \
;         __builtin_amdgcn_global_load_lds((const unsigned*)((const char*)(gbase) + (voff)[_i]), (LAS unsigned*)(lds + (bufoff) + ldsw + _i * 8192), 16, 0, 0); } while (0)
; #define PG8_LDA(dst, b, h) do { _Pragma("unroll") for (int m = 0; m < 4; ++m) _Pragma("unroll") for (int k = 0; k < 2; ++k) dst[m][k] = *(const LAS bf16x8*)(lds + PG8_SA(b, h) + aoff + m * 2048 + k * 1024); } while (0)
; #define PG8_LDB(dst, b, h) do { _Pragma("unroll") for (int n = 0; n < 2; ++n) _Pragma("unroll") for (int k = 0; k < 2; ++k) dst[n][k] = *(const LAS bf16x8*)(lds + PG8_SB(b, h) + boff + n * 2048 + k * 1024); } while (0)
; #define PG8_MMA(ai, bj, At, Bt) do { __builtin_amdgcn_s_setprio(1); _Pragma("unroll") for (int m = 0; m < 4; ++m) _Pragma("unroll") for (int n = 0; n < 2; ++n) _Pragma("unroll") for (int k = 0; k < 2; ++k) \
;         acc[ai][bj][m][n] = __builtin_amdgcn_mfma_f32_16x16x32_bf16(Bt[n][k], At[m][k], acc[ai][bj][m][n], 0, 0, 0); __builtin_amdgcn_s_setprio(0); } while (0)
; #define PG8_WAIT_V(n) asm volatile("s_waitcnt vmcnt(" #n ")" ::: "memory")
; #define PG8_WAIT_L(n) asm volatile("s_waitcnt lgkmcnt(" #n ")" ::: "memory")
; #define PG8_BAR __builtin_amdgcn_s_barrier()
; #define PG8_SCHED __builtin_amdgcn_sched_barrier(0)
; template <class Epi>
; __device__ __forceinline__ void gemm_phase(LAS unsigned char* lds, const Gemm g, const StaticOrder& S, const Epi& E, const bool perm) {
;     ...
;             PG8_BAR; PG8_WAIT_L(0); PG8_MMA(1, 0, At, B0); PG8_BAR; PG8_SCHED;
;             PG8_STAGE(PG8_SB(0, 1), b2 + hstep, voffB);
;             PG8_WAIT_V(6); PG8_BAR; PG8_MMA(1, 1, At, B1); PG8_BAR;
;             PG8_LDB(B0, 1, 0); PG8_SCHED; PG8_LDA(At, 1, 0); PG8_STAGE(PG8_SA(0, 1), a2 + hstep, voffA);
;             PG8_WAIT_L(8); PG8_BAR; PG8_WAIT_L(0); PG8_MMA(0, 0, At, B0); PG8_BAR; PG8_SCHED;
	v_mfma_f32_16x16x32_bf16 v[60:63], v[128:131], v[144:147], 0
	v_mfma_f32_16x16x32_bf16 v[56:59], v[136:139], v[144:147], 0
	v_mfma_f32_16x16x32_bf16 v[44:47], v[128:131], v[152:155], 0
	v_mfma_f32_16x16x32_bf16 v[40:43], v[136:139], v[152:155], 0
	v_mfma_f32_16x16x32_bf16 v[28:31], v[128:131], v[160:163], 0
	v_mfma_f32_16x16x32_bf16 v[24:27], v[136:139], v[160:163], 0
	v_mfma_f32_16x16x32_bf16 v[12:15], v[128:131], v[168:171], 0
	v_mfma_f32_16x16x32_bf16 v[8:11], v[136:139], v[168:171], 0
	v_mfma_f32_16x16x32_bf16 v[60:63], v[132:135], v[148:151], v[60:63]
	v_mfma_f32_16x16x32_bf16 v[56:59], v[140:143], v[148:151], v[56:59]
	v_mfma_f32_16x16x32_bf16 v[44:47], v[132:135], v[156:159], v[44:47]
	v_mfma_f32_16x16x32_bf16 v[40:43], v[140:143], v[156:159], v[40:43]
	v_mfma_f32_16x16x32_bf16 v[28:31], v[132:135], v[164:167], v[28:31]
	v_mfma_f32_16x16x32_bf16 v[24:27], v[140:143], v[164:167], v[24:27]
	v_mfma_f32_16x16x32_bf16 v[12:15], v[132:135], v[172:175], v[12:15]
	v_mfma_f32_16x16x32_bf16 v[8:11], v[140:143], v[172:175], v[8:11]
	v_mfma_f32_16x16x32_bf16 v[52:55], v[176:179], v[144:147], 0
	v_mfma_f32_16x16x32_bf16 v[48:51], v[222:225], v[144:147], 0
	v_mfma_f32_16x16x32_bf16 v[36:39], v[176:179], v[152:155], 0
	v_mfma_f32_16x16x32_bf16 v[32:35], v[222:225], v[152:155], 0
	v_mfma_f32_16x16x32_bf16 v[20:23], v[176:179], v[160:163], 0
	v_mfma_f32_16x16x32_bf16 v[16:19], v[222:225], v[160:163], 0
	v_mfma_f32_16x16x32_bf16 v[4:7], v[176:179], v[168:171], 0
	v_mfma_f32_16x16x32_bf16 v[0:3], v[222:225], v[168:171], 0
	v_mfma_f32_16x16x32_bf16 v[52:55], v[180:183], v[148:151], v[52:55]
	v_mfma_f32_16x16x32_bf16 v[48:51], v[226:229], v[148:151], v[48:51]
	v_mfma_f32_16x16x32_bf16 v[36:39], v[180:183], v[156:159], v[36:39]
	v_mfma_f32_16x16x32_bf16 v[32:35], v[226:229], v[156:159], v[32:35]
	v_mfma_f32_16x16x32_bf16 v[20:23], v[180:183], v[164:167], v[20:23]
	v_mfma_f32_16x16x32_bf16 v[16:19], v[226:229], v[164:167], v[16:19]
	v_mfma_f32_16x16x32_bf16 v[4:7], v[180:183], v[172:175], v[4:7]
	v_mfma_f32_16x16x32_bf16 v[0:3], v[226:229], v[172:175], v[0:3]
	s_add_i32 s40, 0, 0x18000
	v_add_u32_e32 v140, s40, v245
	s_barrier
	ds_read_b128 v[128:131], v140
	ds_read_b128 v[132:135], v140 offset:1024
	ds_read_b128 v[136:139], v140 offset:2048
	ds_read_b128 v[140:143], v140 offset:3072
	s_add_u32 s22, s22, s80
	s_addc_u32 s23, s23, s81
	s_mov_b32 m0, s34
	v_lshl_add_u64 v[176:177], s[22:23], 0, v[210:211]
	ds_read_b128 v[144:147], v248 offset:32768
	ds_read_b128 v[148:151], v248 offset:33792
	ds_read_b128 v[152:155], v248 offset:34816
	ds_read_b128 v[156:159], v248 offset:35840
	ds_read_b128 v[160:163], v248 offset:36864
	ds_read_b128 v[164:167], v248 offset:37888
	ds_read_b128 v[168:171], v248 offset:38912
	ds_read_b128 v[172:175], v248 offset:39936
	global_load_lds_dwordx4 v[176:177], off
	v_lshl_add_u64 v[176:177], s[22:23], 0, v[206:207]
	s_mov_b32 m0, s35
	s_nop 0
	global_load_lds_dwordx4 v[176:177], off
	s_add_i32 s22, 0, 0x1c000
	s_add_i32 s23, s40, s31
	v_add_u32_e32 v184, s22, v245
	ds_read_b128 v[176:179], v184
	ds_read_b128 v[180:183], v184 offset:1024
	ds_read_b128 v[222:225], v184 offset:2048
	ds_read_b128 v[226:229], v184 offset:3072
	s_waitcnt vmcnt(8)
	s_waitcnt lgkmcnt(0)
	s_barrier
	v_mfma_f32_16x16x32_bf16 v[124:127], v[128:131], v[144:147], v[124:127]
	v_mfma_f32_16x16x32_bf16 v[120:123], v[136:139], v[144:147], v[120:123]
	v_mfma_f32_16x16x32_bf16 v[108:111], v[128:131], v[152:155], v[108:111]
	v_mfma_f32_16x16x32_bf16 v[104:107], v[136:139], v[152:155], v[104:107]
	v_mfma_f32_16x16x32_bf16 v[92:95], v[128:131], v[160:163], v[92:95]
	v_mfma_f32_16x16x32_bf16 v[88:91], v[136:139], v[160:163], v[88:91]
	v_mfma_f32_16x16x32_bf16 v[76:79], v[128:131], v[168:171], v[76:79]
	v_mfma_f32_16x16x32_bf16 v[72:75], v[136:139], v[168:171], v[72:75]
	v_mfma_f32_16x16x32_bf16 v[124:127], v[132:135], v[148:151], v[124:127]
	v_mfma_f32_16x16x32_bf16 v[120:123], v[140:143], v[148:151], v[120:123]
	v_mfma_f32_16x16x32_bf16 v[108:111], v[132:135], v[156:159], v[108:111]
	v_mfma_f32_16x16x32_bf16 v[104:107], v[140:143], v[156:159], v[104:107]
	v_mfma_f32_16x16x32_bf16 v[92:95], v[132:135], v[164:167], v[92:95]
	v_mfma_f32_16x16x32_bf16 v[88:91], v[140:143], v[164:167], v[88:91]
	v_mfma_f32_16x16x32_bf16 v[76:79], v[132:135], v[172:175], v[76:79]
	v_mfma_f32_16x16x32_bf16 v[72:75], v[140:143], v[172:175], v[72:75]
	v_mfma_f32_16x16x32_bf16 v[116:119], v[176:179], v[144:147], v[116:119]
	v_mfma_f32_16x16x32_bf16 v[112:115], v[222:225], v[144:147], v[112:115]
	v_mfma_f32_16x16x32_bf16 v[100:103], v[176:179], v[152:155], v[100:103]
	v_mfma_f32_16x16x32_bf16 v[96:99], v[222:225], v[152:155], v[96:99]
	v_mfma_f32_16x16x32_bf16 v[84:87], v[176:179], v[160:163], v[84:87]
	v_mfma_f32_16x16x32_bf16 v[80:83], v[222:225], v[160:163], v[80:83]
	v_mfma_f32_16x16x32_bf16 v[68:71], v[176:179], v[168:171], v[68:71]
	v_mfma_f32_16x16x32_bf16 v[64:67], v[222:225], v[168:171], v[64:67]
	v_mfma_f32_16x16x32_bf16 v[116:119], v[180:183], v[148:151], v[116:119]
	v_mfma_f32_16x16x32_bf16 v[112:115], v[226:229], v[148:151], v[112:115]
	v_mfma_f32_16x16x32_bf16 v[100:103], v[180:183], v[156:159], v[100:103]
	v_mfma_f32_16x16x32_bf16 v[96:99], v[226:229], v[156:159], v[96:99]
	v_mfma_f32_16x16x32_bf16 v[84:87], v[180:183], v[164:167], v[84:87]
	v_mfma_f32_16x16x32_bf16 v[80:83], v[226:229], v[164:167], v[80:83]
	v_mfma_f32_16x16x32_bf16 v[68:71], v[180:183], v[172:175], v[68:71]
	v_mfma_f32_16x16x32_bf16 v[64:67], v[226:229], v[172:175], v[64:67]
	s_barrier
; #define PG8_STAGE(bufoff, gbase, voff) do { _Pragma("unroll") for (int _i = 0; _i < 2; ++_i) \
;         __builtin_amdgcn_global_load_lds((const unsigned*)((const char*)(gbase) + (voff)[_i]), (LAS unsigned*)(lds + (bufoff) + ldsw + _i * 8192), 16, 0, 0); } while (0)
; #define PG8_LDA(dst, b, h) do { _Pragma("unroll") for (int m = 0; m < 4; ++m) _Pragma("unroll") for (int k = 0; k < 2; ++k) dst[m][k] = *(const LAS bf16x8*)(lds + PG8_SA(b, h) + aoff + m * 2048 + k * 1024); } while (0)
; #define PG8_LDB(dst, b, h) do { _Pragma("unroll") for (int n = 0; n < 2; ++n) _Pragma("unroll") for (int k = 0; k < 2; ++k) dst[n][k] = *(const LAS bf16x8*)(lds + PG8_SB(b, h) + boff + n * 2048 + k * 1024); } while (0)
; #define PG8_MMA(ai, bj, At, Bt) do { __builtin_amdgcn_s_setprio(1); _Pragma("unroll") for (int m = 0; m < 4; ++m) _Pragma("unroll") for (int n = 0; n < 2; ++n) _Pragma("unroll") for (int k = 0; k < 2; ++k) \
;         acc[ai][bj][m][n] = __builtin_amdgcn_mfma_f32_16x16x32_bf16(Bt[n][k], At[m][k], acc[ai][bj][m][n], 0, 0, 0); __builtin_amdgcn_s_setprio(0); } while (0)
; #define PG8_WAIT_V(n) asm volatile("s_waitcnt vmcnt(" #n ")" ::: "memory")
; #define PG8_WAIT_L(n) asm volatile("s_waitcnt lgkmcnt(" #n ")" ::: "memory")
; #define PG8_BAR __builtin_amdgcn_s_barrier()
; #define PG8_SCHED __builtin_amdgcn_sched_barrier(0)
; template <class Epi>
; __device__ __forceinline__ void gemm_phase(LAS unsigned char* lds, const Gemm g, const StaticOrder& S, const Epi& E, const bool perm) {
;     ...
;             PG8_LDB(B0, 0, 0); PG8_SCHED; PG8_LDA(At, 0, 0); PG8_STAGE(PG8_SA(1, 1), a1 + hstep, voffA);
;             PG8_WAIT_L(8); PG8_BAR; PG8_WAIT_L(0); PG8_MMA(0, 0, At, B0); PG8_BAR; PG8_SCHED;
;     ...
;             PG8_LDB(B1, 1, 1); PG8_STAGE(PG8_SB(1, 0), b3, voffB);
;             PG8_BAR; PG8_WAIT_L(0); PG8_MMA(0, 1, At, B1); PG8_BAR;
;             PG8_LDA(At, 1, 1); PG8_STAGE(PG8_SA(1, 0), a3, voffA);
;             PG8_BAR; PG8_WAIT_L(0); PG8_MMA(1, 0, At, B0); PG8_BAR; PG8_SCHED;
;             PG8_STAGE(PG8_SB(1, 1), b3 + hstep, voffB);
;             PG8_WAIT_V(6); PG8_BAR; PG8_MMA(1, 1, At, B1); PG8_BAR;
	ds_read_b128 v[144:147], v248 offset:49152
	ds_read_b128 v[148:151], v248 offset:50176
	ds_read_b128 v[152:155], v248 offset:51200
	ds_read_b128 v[156:159], v248 offset:52224
	ds_read_b128 v[160:163], v248 offset:53248
	ds_read_b128 v[164:167], v248 offset:54272
	ds_read_b128 v[168:171], v248 offset:55296
	ds_read_b128 v[172:175], v248 offset:56320
	v_lshl_add_u64 v[230:231], v[230:231], 0, s[74:75]
	s_mov_b32 m0, s23
	s_nop 0
	global_load_lds_dwordx4 v[230:231], off
	v_lshl_add_u64 v[230:231], v[232:233], 0, s[74:75]
	s_add_i32 m0, s23, 0x2000
	s_nop 0
	global_load_lds_dwordx4 v[230:231], off
	v_lshl_add_u64 v[230:231], v[250:251], 0, s[74:75]
	s_mov_b32 m0, s14
	s_nop 0
	global_load_lds_dwordx4 v[230:231], off
	v_lshl_add_u64 v[230:231], v[252:253], 0, s[74:75]
	s_mov_b32 m0, s15
	s_nop 0
	global_load_lds_dwordx4 v[230:231], off
	s_add_i32 s22, s22, s31
	v_lshl_add_u64 v[230:231], v[238:239], 0, s[74:75]
	s_mov_b32 m0, s22
	s_nop 0
	global_load_lds_dwordx4 v[230:231], off
	v_lshl_add_u64 v[230:231], v[240:241], 0, s[74:75]
	s_add_i32 m0, s22, 0x2000
	s_nop 0
	global_load_lds_dwordx4 v[230:231], off
	s_waitcnt vmcnt(8)
	s_waitcnt lgkmcnt(0)
	s_barrier
	v_mfma_f32_16x16x32_bf16 v[60:63], v[128:131], v[144:147], v[60:63]
	v_mfma_f32_16x16x32_bf16 v[56:59], v[136:139], v[144:147], v[56:59]
	v_mfma_f32_16x16x32_bf16 v[44:47], v[128:131], v[152:155], v[44:47]
	v_mfma_f32_16x16x32_bf16 v[40:43], v[136:139], v[152:155], v[40:43]
	v_mfma_f32_16x16x32_bf16 v[28:31], v[128:131], v[160:163], v[28:31]
	v_mfma_f32_16x16x32_bf16 v[24:27], v[136:139], v[160:163], v[24:27]
	v_mfma_f32_16x16x32_bf16 v[12:15], v[128:131], v[168:171], v[12:15]
	v_mfma_f32_16x16x32_bf16 v[8:11], v[136:139], v[168:171], v[8:11]
	v_mfma_f32_16x16x32_bf16 v[60:63], v[132:135], v[148:151], v[60:63]
	v_mfma_f32_16x16x32_bf16 v[56:59], v[140:143], v[148:151], v[56:59]
	v_mfma_f32_16x16x32_bf16 v[44:47], v[132:135], v[156:159], v[44:47]
	v_mfma_f32_16x16x32_bf16 v[40:43], v[140:143], v[156:159], v[40:43]
	v_mfma_f32_16x16x32_bf16 v[28:31], v[132:135], v[164:167], v[28:31]
	v_mfma_f32_16x16x32_bf16 v[24:27], v[140:143], v[164:167], v[24:27]
	v_mfma_f32_16x16x32_bf16 v[12:15], v[132:135], v[172:175], v[12:15]
	v_mfma_f32_16x16x32_bf16 v[8:11], v[140:143], v[172:175], v[8:11]
	v_mfma_f32_16x16x32_bf16 v[52:55], v[176:179], v[144:147], v[52:55]
	v_mfma_f32_16x16x32_bf16 v[48:51], v[222:225], v[144:147], v[48:51]
	v_mfma_f32_16x16x32_bf16 v[36:39], v[176:179], v[152:155], v[36:39]
	v_mfma_f32_16x16x32_bf16 v[32:35], v[222:225], v[152:155], v[32:35]
	v_mfma_f32_16x16x32_bf16 v[20:23], v[176:179], v[160:163], v[20:23]
	v_mfma_f32_16x16x32_bf16 v[16:19], v[222:225], v[160:163], v[16:19]
	v_mfma_f32_16x16x32_bf16 v[4:7], v[176:179], v[168:171], v[4:7]
	v_mfma_f32_16x16x32_bf16 v[0:3], v[222:225], v[168:171], v[0:3]
	v_mfma_f32_16x16x32_bf16 v[52:55], v[180:183], v[148:151], v[52:55]
	v_mfma_f32_16x16x32_bf16 v[48:51], v[226:229], v[148:151], v[48:51]
	v_mfma_f32_16x16x32_bf16 v[36:39], v[180:183], v[156:159], v[36:39]
	v_mfma_f32_16x16x32_bf16 v[32:35], v[226:229], v[156:159], v[32:35]
	v_mfma_f32_16x16x32_bf16 v[20:23], v[180:183], v[164:167], v[20:23]
	v_mfma_f32_16x16x32_bf16 v[16:19], v[226:229], v[164:167], v[16:19]
	v_mfma_f32_16x16x32_bf16 v[4:7], v[180:183], v[172:175], v[4:7]
	v_mfma_f32_16x16x32_bf16 v[0:3], v[226:229], v[172:175], v[0:3]
	s_addk_i32 s79, 0x80
	s_add_u32 s6, s6, 0x100
	s_addc_u32 s7, s7, 0
	s_add_u32 s55, s55, 0x100
	s_addc_u32 s78, s78, 0
	s_cmp_ge_u32 s61, s65
	s_mov_b32 s60, s61
	s_barrier
	s_cbranch_scc1 .LBB0_470
	s_branch .LBB0_463
.LBB0_462:
	s_add_i32 s61, s60, 2
	s_add_u32 s22, s6, 0x80
	s_addc_u32 s23, s7, 0
	s_add_i32 s40, 0, 0x10000
	v_add_u32_e32 v140, s40, v245
	s_waitcnt lgkmcnt(0)
	ds_read_b128 v[128:131], v140
	ds_read_b128 v[132:135], v140 offset:1024
	ds_read_b128 v[136:139], v140 offset:2048
	ds_read_b128 v[140:143], v140 offset:3072
	s_cmp_eq_u32 s27, s60
	s_cselect_b32 s23, s1, s23
	s_cselect_b32 s22, s0, s22
	s_cselect_b32 s47, s13, s78
	s_cselect_b32 s46, s12, s55
	v_lshl_add_u64 v[176:177], s[6:7], 0, v[214:215]
	s_add_i32 m0, s36, 0xc000
	ds_read_b128 v[144:147], v248
	ds_read_b128 v[148:151], v248 offset:1024
	ds_read_b128 v[152:155], v248 offset:2048
	ds_read_b128 v[156:159], v248 offset:3072
	ds_read_b128 v[160:163], v248 offset:4096
	ds_read_b128 v[164:167], v248 offset:5120
	ds_read_b128 v[168:171], v248 offset:6144
	ds_read_b128 v[172:175], v248 offset:7168
	global_load_lds_dwordx4 v[176:177], off
	v_lshl_add_u64 v[176:177], s[6:7], 0, v[216:217]
	s_add_i32 m0, s36, 0xe000
	s_nop 0
	global_load_lds_dwordx4 v[176:177], off
	s_add_i32 s60, 0, 0x14000
	s_add_i32 s40, s40, s31
	v_add_u32_e32 v184, s60, v245
	ds_read_b128 v[176:179], v184
	ds_read_b128 v[180:183], v184 offset:1024
	ds_read_b128 v[222:225], v184 offset:2048
	ds_read_b128 v[226:229], v184 offset:3072
	s_waitcnt vmcnt(8)
	s_waitcnt lgkmcnt(0)
	s_barrier
; #define PG8_STAGE(bufoff, gbase, voff) do { _Pragma("unroll") for (int _i = 0; _i < 2; ++_i) \
;         __builtin_amdgcn_global_load_lds((const unsigned*)((const char*)(gbase) + (voff)[_i]), (LAS unsigned*)(lds + (bufoff) + ldsw + _i * 8192), 16, 0, 0); } while (0)
; #define PG8_LDA(dst, b, h) do { _Pragma("unroll") for (int m = 0; m < 4; ++m) _Pragma("unroll") for (int k = 0; k < 2; ++k) dst[m][k] = *(const LAS bf16x8*)(lds + PG8_SA(b, h) + aoff + m * 2048 + k * 1024); } while (0)
; #define PG8_LDB(dst, b, h) do { _Pragma("unroll") for (int n = 0; n < 2; ++n) _Pragma("unroll") for (int k = 0; k < 2; ++k) dst[n][k] = *(const LAS bf16x8*)(lds + PG8_SB(b, h) + boff + n * 2048 + k * 1024); } while (0)
; #define PG8_MMA(ai, bj, At, Bt) do { __builtin_amdgcn_s_setprio(1); _Pragma("unroll") for (int m = 0; m < 4; ++m) _Pragma("unroll") for (int n = 0; n < 2; ++n) _Pragma("unroll") for (int k = 0; k < 2; ++k) \
;         acc[ai][bj][m][n] = __builtin_amdgcn_mfma_f32_16x16x32_bf16(Bt[n][k], At[m][k], acc[ai][bj][m][n], 0, 0, 0); __builtin_amdgcn_s_setprio(0); } while (0)
; #define PG8_WAIT_V(n) asm volatile("s_waitcnt vmcnt(" #n ")" ::: "memory")
; #define PG8_WAIT_L(n) asm volatile("s_waitcnt lgkmcnt(" #n ")" ::: "memory")
; #define PG8_BAR __builtin_amdgcn_s_barrier()
; #define PG8_SCHED __builtin_amdgcn_sched_barrier(0)
; template <class Epi>
; __device__ __forceinline__ void gemm_phase(LAS unsigned char* lds, const Gemm g, const StaticOrder& S, const Epi& E, const bool perm) {
;     ...
;             PG8_WAIT_L(8); PG8_BAR; PG8_WAIT_L(0); PG8_MMA(0, 0, At, B0); PG8_BAR; PG8_SCHED;
;             PG8_LDB(B1, 0, 1); PG8_STAGE(PG8_SB(0, 0), b2, voffB);
;             PG8_BAR; PG8_WAIT_L(0); PG8_MMA(0, 1, At, B1); PG8_BAR;
;             PG8_LDA(At, 0, 1); PG8_STAGE(PG8_SA(0, 0), a2, voffA);
;             PG8_BAR; PG8_WAIT_L(0); PG8_MMA(1, 0, At, B0); PG8_BAR; PG8_SCHED;
;             PG8_STAGE(PG8_SB(0, 1), b2 + hstep, voffB);
;             PG8_WAIT_V(6); PG8_BAR; PG8_MMA(1, 1, At, B1); PG8_BAR;
	v_mfma_f32_16x16x32_bf16 v[124:127], v[128:131], v[144:147], v[124:127]
	v_mfma_f32_16x16x32_bf16 v[120:123], v[136:139], v[144:147], v[120:123]
	v_mfma_f32_16x16x32_bf16 v[108:111], v[128:131], v[152:155], v[108:111]
	v_mfma_f32_16x16x32_bf16 v[104:107], v[136:139], v[152:155], v[104:107]
	v_mfma_f32_16x16x32_bf16 v[92:95], v[128:131], v[160:163], v[92:95]
	v_mfma_f32_16x16x32_bf16 v[88:91], v[136:139], v[160:163], v[88:91]
	v_mfma_f32_16x16x32_bf16 v[76:79], v[128:131], v[168:171], v[76:79]
	v_mfma_f32_16x16x32_bf16 v[72:75], v[136:139], v[168:171], v[72:75]
	v_mfma_f32_16x16x32_bf16 v[124:127], v[132:135], v[148:151], v[124:127]
	v_mfma_f32_16x16x32_bf16 v[120:123], v[140:143], v[148:151], v[120:123]
	v_mfma_f32_16x16x32_bf16 v[108:111], v[132:135], v[156:159], v[108:111]
	v_mfma_f32_16x16x32_bf16 v[104:107], v[140:143], v[156:159], v[104:107]
	v_mfma_f32_16x16x32_bf16 v[92:95], v[132:135], v[164:167], v[92:95]
	v_mfma_f32_16x16x32_bf16 v[88:91], v[140:143], v[164:167], v[88:91]
	v_mfma_f32_16x16x32_bf16 v[76:79], v[132:135], v[172:175], v[76:79]
	v_mfma_f32_16x16x32_bf16 v[72:75], v[140:143], v[172:175], v[72:75]
	v_mfma_f32_16x16x32_bf16 v[116:119], v[176:179], v[144:147], v[116:119]
	v_mfma_f32_16x16x32_bf16 v[112:115], v[222:225], v[144:147], v[112:115]
	v_mfma_f32_16x16x32_bf16 v[100:103], v[176:179], v[152:155], v[100:103]
	v_mfma_f32_16x16x32_bf16 v[96:99], v[222:225], v[152:155], v[96:99]
	v_mfma_f32_16x16x32_bf16 v[84:87], v[176:179], v[160:163], v[84:87]
	v_mfma_f32_16x16x32_bf16 v[80:83], v[222:225], v[160:163], v[80:83]
	v_mfma_f32_16x16x32_bf16 v[68:71], v[176:179], v[168:171], v[68:71]
	v_mfma_f32_16x16x32_bf16 v[64:67], v[222:225], v[168:171], v[64:67]
	v_mfma_f32_16x16x32_bf16 v[116:119], v[180:183], v[148:151], v[116:119]
	v_mfma_f32_16x16x32_bf16 v[112:115], v[226:229], v[148:151], v[112:115]
	v_mfma_f32_16x16x32_bf16 v[100:103], v[180:183], v[156:159], v[100:103]
	v_mfma_f32_16x16x32_bf16 v[96:99], v[226:229], v[156:159], v[96:99]
	v_mfma_f32_16x16x32_bf16 v[84:87], v[180:183], v[164:167], v[84:87]
	v_mfma_f32_16x16x32_bf16 v[80:83], v[226:229], v[164:167], v[80:83]
	v_mfma_f32_16x16x32_bf16 v[68:71], v[180:183], v[172:175], v[68:71]
	v_mfma_f32_16x16x32_bf16 v[64:67], v[226:229], v[172:175], v[64:67]
	s_barrier
	ds_read_b128 v[144:147], v248 offset:16384
	ds_read_b128 v[148:151], v248 offset:17408
	ds_read_b128 v[152:155], v248 offset:18432
	ds_read_b128 v[156:159], v248 offset:19456
	ds_read_b128 v[160:163], v248 offset:20480
	ds_read_b128 v[164:167], v248 offset:21504
	ds_read_b128 v[168:171], v248 offset:22528
	ds_read_b128 v[172:175], v248 offset:23552
	v_lshl_add_u64 v[230:231], s[46:47], 0, v[212:213]
	s_mov_b32 m0, s40
	s_nop 0
	global_load_lds_dwordx4 v[230:231], off
	v_lshl_add_u64 v[232:233], s[46:47], 0, v[208:209]
	s_add_i32 m0, s40, 0x2000
	s_nop 0
	global_load_lds_dwordx4 v[232:233], off
	v_lshl_add_u64 v[250:251], s[22:23], 0, v[210:211]
	s_mov_b32 m0, s36
	s_nop 0
	global_load_lds_dwordx4 v[250:251], off
	v_lshl_add_u64 v[252:253], s[22:23], 0, v[206:207]
	s_mov_b32 m0, s37
	s_nop 0
	global_load_lds_dwordx4 v[252:253], off
	s_add_u32 s40, s46, s80
	s_addc_u32 s41, s47, s81
	s_add_i32 s46, s60, s31
	v_lshl_add_u64 v[238:239], s[40:41], 0, v[212:213]
	s_mov_b32 m0, s46
	v_lshl_add_u64 v[240:241], s[40:41], 0, v[208:209]
	global_load_lds_dwordx4 v[238:239], off
	s_add_i32 m0, s46, 0x2000
	s_nop 0
	global_load_lds_dwordx4 v[240:241], off
	s_waitcnt vmcnt(8)
	s_waitcnt lgkmcnt(0)
	s_barrier
	v_mfma_f32_16x16x32_bf16 v[60:63], v[128:131], v[144:147], v[60:63]
	v_mfma_f32_16x16x32_bf16 v[56:59], v[136:139], v[144:147], v[56:59]
	v_mfma_f32_16x16x32_bf16 v[44:47], v[128:131], v[152:155], v[44:47]
	v_mfma_f32_16x16x32_bf16 v[40:43], v[136:139], v[152:155], v[40:43]
	v_mfma_f32_16x16x32_bf16 v[28:31], v[128:131], v[160:163], v[28:31]
	v_mfma_f32_16x16x32_bf16 v[24:27], v[136:139], v[160:163], v[24:27]
	v_mfma_f32_16x16x32_bf16 v[12:15], v[128:131], v[168:171], v[12:15]
	v_mfma_f32_16x16x32_bf16 v[8:11], v[136:139], v[168:171], v[8:11]
	v_mfma_f32_16x16x32_bf16 v[60:63], v[132:135], v[148:151], v[60:63]
	v_mfma_f32_16x16x32_bf16 v[56:59], v[140:143], v[148:151], v[56:59]
	v_mfma_f32_16x16x32_bf16 v[44:47], v[132:135], v[156:159], v[44:47]
	v_mfma_f32_16x16x32_bf16 v[40:43], v[140:143], v[156:159], v[40:43]
	v_mfma_f32_16x16x32_bf16 v[28:31], v[132:135], v[164:167], v[28:31]
	v_mfma_f32_16x16x32_bf16 v[24:27], v[140:143], v[164:167], v[24:27]
	v_mfma_f32_16x16x32_bf16 v[12:15], v[132:135], v[172:175], v[12:15]
	v_mfma_f32_16x16x32_bf16 v[8:11], v[140:143], v[172:175], v[8:11]
	v_mfma_f32_16x16x32_bf16 v[52:55], v[176:179], v[144:147], v[52:55]
	v_mfma_f32_16x16x32_bf16 v[48:51], v[222:225], v[144:147], v[48:51]
	v_mfma_f32_16x16x32_bf16 v[36:39], v[176:179], v[152:155], v[36:39]
	v_mfma_f32_16x16x32_bf16 v[32:35], v[222:225], v[152:155], v[32:35]
	v_mfma_f32_16x16x32_bf16 v[20:23], v[176:179], v[160:163], v[20:23]
	v_mfma_f32_16x16x32_bf16 v[16:19], v[222:225], v[160:163], v[16:19]
	v_mfma_f32_16x16x32_bf16 v[4:7], v[176:179], v[168:171], v[4:7]
	v_mfma_f32_16x16x32_bf16 v[0:3], v[222:225], v[168:171], v[0:3]
	v_mfma_f32_16x16x32_bf16 v[52:55], v[180:183], v[148:151], v[52:55]
	v_mfma_f32_16x16x32_bf16 v[48:51], v[226:229], v[148:151], v[48:51]
	v_mfma_f32_16x16x32_bf16 v[36:39], v[180:183], v[156:159], v[36:39]
	v_mfma_f32_16x16x32_bf16 v[32:35], v[226:229], v[156:159], v[32:35]
	v_mfma_f32_16x16x32_bf16 v[20:23], v[180:183], v[164:167], v[20:23]
	v_mfma_f32_16x16x32_bf16 v[16:19], v[226:229], v[164:167], v[16:19]
	v_mfma_f32_16x16x32_bf16 v[4:7], v[180:183], v[172:175], v[4:7]
	v_mfma_f32_16x16x32_bf16 v[0:3], v[226:229], v[172:175], v[0:3]
	s_add_i32 s40, 0, 0x18000
	v_add_u32_e32 v140, s40, v245
	s_barrier
; #define PG8_STAGE(bufoff, gbase, voff) do { _Pragma("unroll") for (int _i = 0; _i < 2; ++_i) \
;         __builtin_amdgcn_global_load_lds((const unsigned*)((const char*)(gbase) + (voff)[_i]), (LAS unsigned*)(lds + (bufoff) + ldsw + _i * 8192), 16, 0, 0); } while (0)
; #define PG8_LDA(dst, b, h) do { _Pragma("unroll") for (int m = 0; m < 4; ++m) _Pragma("unroll") for (int k = 0; k < 2; ++k) dst[m][k] = *(const LAS bf16x8*)(lds + PG8_SA(b, h) + aoff + m * 2048 + k * 1024); } while (0)
; #define PG8_LDB(dst, b, h) do { _Pragma("unroll") for (int n = 0; n < 2; ++n) _Pragma("unroll") for (int k = 0; k < 2; ++k) dst[n][k] = *(const LAS bf16x8*)(lds + PG8_SB(b, h) + boff + n * 2048 + k * 1024); } while (0)
; #define PG8_MMA(ai, bj, At, Bt) do { __builtin_amdgcn_s_setprio(1); _Pragma("unroll") for (int m = 0; m < 4; ++m) _Pragma("unroll") for (int n = 0; n < 2; ++n) _Pragma("unroll") for (int k = 0; k < 2; ++k) \
;         acc[ai][bj][m][n] = __builtin_amdgcn_mfma_f32_16x16x32_bf16(Bt[n][k], At[m][k], acc[ai][bj][m][n], 0, 0, 0); __builtin_amdgcn_s_setprio(0); } while (0)
; #define PG8_WAIT_V(n) asm volatile("s_waitcnt vmcnt(" #n ")" ::: "memory")
; #define PG8_WAIT_L(n) asm volatile("s_waitcnt lgkmcnt(" #n ")" ::: "memory")
; #define PG8_BAR __builtin_amdgcn_s_barrier()
; #define PG8_SCHED __builtin_amdgcn_sched_barrier(0)
; template <class Epi>
; __device__ __forceinline__ void gemm_phase(LAS unsigned char* lds, const Gemm g, const StaticOrder& S, const Epi& E, const bool perm) {
;     ...
;             PG8_LDB(B0, 1, 0); PG8_SCHED; PG8_LDA(At, 1, 0); PG8_STAGE(PG8_SA(0, 1), a2 + hstep, voffA);
;             PG8_WAIT_L(8); PG8_BAR; PG8_WAIT_L(0); PG8_MMA(0, 0, At, B0); PG8_BAR; PG8_SCHED;
;             PG8_LDB(B1, 1, 1); PG8_STAGE(PG8_SB(1, 0), b3, voffB);
;             PG8_BAR; PG8_WAIT_L(0); PG8_MMA(0, 1, At, B1); PG8_BAR;
;             PG8_LDA(At, 1, 1); PG8_STAGE(PG8_SA(1, 0), a3, voffA);
;             PG8_BAR; PG8_WAIT_L(0); PG8_MMA(1, 0, At, B0); PG8_BAR; PG8_SCHED;
;             PG8_STAGE(PG8_SB(1, 1), b3 + hstep, voffB);
;             PG8_WAIT_V(6); PG8_BAR; PG8_MMA(1, 1, At, B1); PG8_BAR;
	ds_read_b128 v[128:131], v140
	ds_read_b128 v[132:135], v140 offset:1024
	ds_read_b128 v[136:139], v140 offset:2048
	ds_read_b128 v[140:143], v140 offset:3072
	s_add_u32 s22, s22, s80
	s_addc_u32 s23, s23, s81
	s_mov_b32 m0, s34
	v_lshl_add_u64 v[176:177], s[22:23], 0, v[210:211]
	ds_read_b128 v[144:147], v248 offset:32768
	ds_read_b128 v[148:151], v248 offset:33792
	ds_read_b128 v[152:155], v248 offset:34816
	ds_read_b128 v[156:159], v248 offset:35840
	ds_read_b128 v[160:163], v248 offset:36864
	ds_read_b128 v[164:167], v248 offset:37888
	ds_read_b128 v[168:171], v248 offset:38912
	ds_read_b128 v[172:175], v248 offset:39936
	global_load_lds_dwordx4 v[176:177], off
	v_lshl_add_u64 v[176:177], s[22:23], 0, v[206:207]
	s_mov_b32 m0, s35
	s_nop 0
	global_load_lds_dwordx4 v[176:177], off
	s_add_i32 s22, 0, 0x1c000
	s_add_i32 s23, s40, s31
	v_add_u32_e32 v184, s22, v245
	ds_read_b128 v[176:179], v184
	ds_read_b128 v[180:183], v184 offset:1024
	ds_read_b128 v[222:225], v184 offset:2048
	ds_read_b128 v[226:229], v184 offset:3072
	s_waitcnt vmcnt(8)
	s_waitcnt lgkmcnt(0)
	s_barrier
	v_mfma_f32_16x16x32_bf16 v[124:127], v[128:131], v[144:147], v[124:127]
	v_mfma_f32_16x16x32_bf16 v[120:123], v[136:139], v[144:147], v[120:123]
	v_mfma_f32_16x16x32_bf16 v[108:111], v[128:131], v[152:155], v[108:111]
	v_mfma_f32_16x16x32_bf16 v[104:107], v[136:139], v[152:155], v[104:107]
	v_mfma_f32_16x16x32_bf16 v[92:95], v[128:131], v[160:163], v[92:95]
	v_mfma_f32_16x16x32_bf16 v[88:91], v[136:139], v[160:163], v[88:91]
	v_mfma_f32_16x16x32_bf16 v[76:79], v[128:131], v[168:171], v[76:79]
	v_mfma_f32_16x16x32_bf16 v[72:75], v[136:139], v[168:171], v[72:75]
	v_mfma_f32_16x16x32_bf16 v[124:127], v[132:135], v[148:151], v[124:127]
	v_mfma_f32_16x16x32_bf16 v[120:123], v[140:143], v[148:151], v[120:123]
	v_mfma_f32_16x16x32_bf16 v[108:111], v[132:135], v[156:159], v[108:111]
	v_mfma_f32_16x16x32_bf16 v[104:107], v[140:143], v[156:159], v[104:107]
	v_mfma_f32_16x16x32_bf16 v[92:95], v[132:135], v[164:167], v[92:95]
	v_mfma_f32_16x16x32_bf16 v[88:91], v[140:143], v[164:167], v[88:91]
	v_mfma_f32_16x16x32_bf16 v[76:79], v[132:135], v[172:175], v[76:79]
	v_mfma_f32_16x16x32_bf16 v[72:75], v[140:143], v[172:175], v[72:75]
	v_mfma_f32_16x16x32_bf16 v[116:119], v[176:179], v[144:147], v[116:119]
	v_mfma_f32_16x16x32_bf16 v[112:115], v[222:225], v[144:147], v[112:115]
	v_mfma_f32_16x16x32_bf16 v[100:103], v[176:179], v[152:155], v[100:103]
	v_mfma_f32_16x16x32_bf16 v[96:99], v[222:225], v[152:155], v[96:99]
	v_mfma_f32_16x16x32_bf16 v[84:87], v[176:179], v[160:163], v[84:87]
	v_mfma_f32_16x16x32_bf16 v[80:83], v[222:225], v[160:163], v[80:83]
	v_mfma_f32_16x16x32_bf16 v[68:71], v[176:179], v[168:171], v[68:71]
	v_mfma_f32_16x16x32_bf16 v[64:67], v[222:225], v[168:171], v[64:67]
	v_mfma_f32_16x16x32_bf16 v[116:119], v[180:183], v[148:151], v[116:119]
	v_mfma_f32_16x16x32_bf16 v[112:115], v[226:229], v[148:151], v[112:115]
	v_mfma_f32_16x16x32_bf16 v[100:103], v[180:183], v[156:159], v[100:103]
	v_mfma_f32_16x16x32_bf16 v[96:99], v[226:229], v[156:159], v[96:99]
	v_mfma_f32_16x16x32_bf16 v[84:87], v[180:183], v[164:167], v[84:87]
	v_mfma_f32_16x16x32_bf16 v[80:83], v[226:229], v[164:167], v[80:83]
	v_mfma_f32_16x16x32_bf16 v[68:71], v[180:183], v[172:175], v[68:71]
	v_mfma_f32_16x16x32_bf16 v[64:67], v[226:229], v[172:175], v[64:67]
	s_barrier
	ds_read_b128 v[144:147], v248 offset:49152
	ds_read_b128 v[148:151], v248 offset:50176
	ds_read_b128 v[152:155], v248 offset:51200
	ds_read_b128 v[156:159], v248 offset:52224
	ds_read_b128 v[160:163], v248 offset:53248
	ds_read_b128 v[164:167], v248 offset:54272
	ds_read_b128 v[168:171], v248 offset:55296
	ds_read_b128 v[172:175], v248 offset:56320
	v_lshl_add_u64 v[230:231], v[230:231], 0, s[74:75]
	s_mov_b32 m0, s23
	s_nop 0
	global_load_lds_dwordx4 v[230:231], off
	v_lshl_add_u64 v[230:231], v[232:233], 0, s[74:75]
	s_add_i32 m0, s23, 0x2000
	s_nop 0
	global_load_lds_dwordx4 v[230:231], off
	v_lshl_add_u64 v[230:231], v[250:251], 0, s[74:75]
	s_mov_b32 m0, s14
	s_nop 0
	global_load_lds_dwordx4 v[230:231], off
	v_lshl_add_u64 v[230:231], v[252:253], 0, s[74:75]
	s_mov_b32 m0, s15
	s_nop 0
	global_load_lds_dwordx4 v[230:231], off
	s_add_i32 s22, s22, s31
	v_lshl_add_u64 v[230:231], v[238:239], 0, s[74:75]
	s_mov_b32 m0, s22
	s_nop 0
	global_load_lds_dwordx4 v[230:231], off
	v_lshl_add_u64 v[230:231], v[240:241], 0, s[74:75]
	s_add_i32 m0, s22, 0x2000
	s_nop 0
	global_load_lds_dwordx4 v[230:231], off
	s_waitcnt vmcnt(8)
	s_waitcnt lgkmcnt(0)
	s_barrier
	v_mfma_f32_16x16x32_bf16 v[60:63], v[128:131], v[144:147], v[60:63]
	v_mfma_f32_16x16x32_bf16 v[56:59], v[136:139], v[144:147], v[56:59]
	v_mfma_f32_16x16x32_bf16 v[44:47], v[128:131], v[152:155], v[44:47]
	v_mfma_f32_16x16x32_bf16 v[40:43], v[136:139], v[152:155], v[40:43]
	v_mfma_f32_16x16x32_bf16 v[28:31], v[128:131], v[160:163], v[28:31]
	v_mfma_f32_16x16x32_bf16 v[24:27], v[136:139], v[160:163], v[24:27]
	v_mfma_f32_16x16x32_bf16 v[12:15], v[128:131], v[168:171], v[12:15]
	v_mfma_f32_16x16x32_bf16 v[8:11], v[136:139], v[168:171], v[8:11]
	v_mfma_f32_16x16x32_bf16 v[60:63], v[132:135], v[148:151], v[60:63]
	v_mfma_f32_16x16x32_bf16 v[56:59], v[140:143], v[148:151], v[56:59]
	v_mfma_f32_16x16x32_bf16 v[44:47], v[132:135], v[156:159], v[44:47]
	v_mfma_f32_16x16x32_bf16 v[40:43], v[140:143], v[156:159], v[40:43]
	v_mfma_f32_16x16x32_bf16 v[28:31], v[132:135], v[164:167], v[28:31]
	v_mfma_f32_16x16x32_bf16 v[24:27], v[140:143], v[164:167], v[24:27]
	v_mfma_f32_16x16x32_bf16 v[12:15], v[132:135], v[172:175], v[12:15]
	v_mfma_f32_16x16x32_bf16 v[8:11], v[140:143], v[172:175], v[8:11]
	v_mfma_f32_16x16x32_bf16 v[52:55], v[176:179], v[144:147], v[52:55]
	v_mfma_f32_16x16x32_bf16 v[48:51], v[222:225], v[144:147], v[48:51]
	v_mfma_f32_16x16x32_bf16 v[36:39], v[176:179], v[152:155], v[36:39]
	v_mfma_f32_16x16x32_bf16 v[32:35], v[222:225], v[152:155], v[32:35]
	v_mfma_f32_16x16x32_bf16 v[20:23], v[176:179], v[160:163], v[20:23]
	v_mfma_f32_16x16x32_bf16 v[16:19], v[222:225], v[160:163], v[16:19]
	v_mfma_f32_16x16x32_bf16 v[4:7], v[176:179], v[168:171], v[4:7]
	v_mfma_f32_16x16x32_bf16 v[0:3], v[222:225], v[168:171], v[0:3]
	v_mfma_f32_16x16x32_bf16 v[52:55], v[180:183], v[148:151], v[52:55]
	v_mfma_f32_16x16x32_bf16 v[48:51], v[226:229], v[148:151], v[48:51]
	v_mfma_f32_16x16x32_bf16 v[36:39], v[180:183], v[156:159], v[36:39]
	v_mfma_f32_16x16x32_bf16 v[32:35], v[226:229], v[156:159], v[32:35]
	v_mfma_f32_16x16x32_bf16 v[20:23], v[180:183], v[164:167], v[20:23]
	v_mfma_f32_16x16x32_bf16 v[16:19], v[226:229], v[164:167], v[16:19]
	v_mfma_f32_16x16x32_bf16 v[4:7], v[180:183], v[172:175], v[4:7]
	v_mfma_f32_16x16x32_bf16 v[0:3], v[226:229], v[172:175], v[0:3]
	s_addk_i32 s79, 0x80
	s_add_u32 s6, s6, 0x100
	s_addc_u32 s7, s7, 0
	s_add_u32 s55, s55, 0x100
	s_addc_u32 s78, s78, 0
	s_cmp_ge_u32 s61, s65
	s_mov_b32 s60, s61
	s_barrier
	s_cbranch_scc1 .LBB0_470

; #define PG8_WAIT_V(n) asm volatile("s_waitcnt vmcnt(" #n ")" ::: "memory")
; #define PG8_BAR __builtin_amdgcn_s_barrier()
; template <class Epi>
; __device__ __forceinline__ void gemm_phase(LAS unsigned char* lds, const Gemm g, const StaticOrder& S, const Epi& E, const bool perm) {
;     ...
;     PG8_WAIT_V(0);
;     if (wr == 0) PG8_BAR;
;     PG8_BAR;
.LBB0_763:
	s_setprio 0
	s_waitcnt vmcnt(0)
	v_readlane_b32 s0, v255, 59
	v_readlane_b32 s40, v255, 42
	s_cmpk_gt_u32 s0, 0xff
	s_movk_i32 s55, 0x3ff
	v_readlane_b32 s41, v255, 43
	s_cbranch_scc1 .LBB0_765
	s_barrier
